# gate: next channel group's gamma/beta vectors and tile rows prefetched into registers right after the pre-MFMA barrier of the current group (group loop top only copies)
# baseline (speedup 1.0000x reference)
.Lgt_g0:
	s_mov_b64 s[100:101], s[36:37]
	v_lshl_add_u64 v[248:249], v[68:69], 0, s[100:101]
	v_lshl_add_u64 v[250:251], v[88:89], 0, s[100:101]
	global_load_dwordx4 v[200:203], v[248:249], off
	global_load_dwordx4 v[204:207], v[248:249], off offset:-16
	global_load_dwordx4 v[208:211], v[250:251], off
	global_load_dwordx4 v[212:215], v[250:251], off offset:-16
	v_mov_b32_e32 v216, 0
	v_mov_b32_e32 v217, 0
	v_mov_b32_e32 v218, 0
	v_mov_b32_e32 v219, 0
	s_and_saveexec_b64 s[100:101], s[6:7]
	v_lshl_add_u64 v[252:253], s[42:43], 0, v[106:107]
	global_load_dwordx4 v[216:219], v[252:253], off
	s_or_b64 exec, exec, s[100:101]
	v_mov_b32_e32 v220, 0
	v_mov_b32_e32 v221, 0
	v_mov_b32_e32 v222, 0
	v_mov_b32_e32 v223, 0
	s_and_saveexec_b64 s[100:101], s[8:9]
	v_lshl_add_u64 v[252:253], s[42:43], 0, v[104:105]
	global_load_dwordx4 v[220:223], v[252:253], off
	s_or_b64 exec, exec, s[100:101]
	v_mov_b32_e32 v224, 0
	v_mov_b32_e32 v225, 0
	v_mov_b32_e32 v226, 0
	v_mov_b32_e32 v227, 0
	s_and_saveexec_b64 s[100:101], s[10:11]
	v_lshl_add_u64 v[252:253], s[42:43], 0, v[102:103]
	global_load_dwordx4 v[224:227], v[252:253], off
	s_or_b64 exec, exec, s[100:101]
	v_mov_b32_e32 v228, 0
	v_mov_b32_e32 v229, 0
	v_mov_b32_e32 v230, 0
	v_mov_b32_e32 v231, 0
	s_and_saveexec_b64 s[100:101], s[12:13]
	v_lshl_add_u64 v[252:253], s[42:43], 0, v[100:101]
	global_load_dwordx4 v[228:231], v[252:253], off
	s_or_b64 exec, exec, s[100:101]
	v_mov_b32_e32 v232, 0
	v_mov_b32_e32 v233, 0
	v_mov_b32_e32 v234, 0
	v_mov_b32_e32 v235, 0
	s_and_saveexec_b64 s[100:101], s[14:15]
	v_lshl_add_u64 v[252:253], s[42:43], 0, v[98:99]
	global_load_dwordx4 v[232:235], v[252:253], off
	s_or_b64 exec, exec, s[100:101]
	v_mov_b32_e32 v236, 0
	v_mov_b32_e32 v237, 0
	v_mov_b32_e32 v238, 0
	v_mov_b32_e32 v239, 0
	s_and_saveexec_b64 s[100:101], s[16:17]
	v_lshl_add_u64 v[252:253], s[42:43], 0, v[96:97]
	global_load_dwordx4 v[236:239], v[252:253], off
	s_or_b64 exec, exec, s[100:101]
	v_mov_b32_e32 v240, 0
	v_mov_b32_e32 v241, 0
	v_mov_b32_e32 v242, 0
	v_mov_b32_e32 v243, 0
	s_and_saveexec_b64 s[100:101], s[18:19]
	v_lshl_add_u64 v[252:253], s[42:43], 0, v[92:93]
	global_load_dwordx4 v[240:243], v[252:253], off
	s_or_b64 exec, exec, s[100:101]
	v_mov_b32_e32 v244, 0
	v_mov_b32_e32 v245, 0
	v_mov_b32_e32 v246, 0
	v_mov_b32_e32 v247, 0
	s_and_saveexec_b64 s[100:101], s[20:21]
	v_lshl_add_u64 v[252:253], s[42:43], 0, v[90:91]
	global_load_dwordx4 v[244:247], v[252:253], off
	s_or_b64 exec, exec, s[100:101]
	s_barrier
	s_branch .LBB0_744

.LBB0_744:
	s_waitcnt vmcnt(0)
	v_mov_b32_e32 v0, v200
	v_mov_b32_e32 v1, v201
	v_mov_b32_e32 v2, v202
	v_mov_b32_e32 v3, v203
	v_mov_b32_e32 v8, v204
	v_mov_b32_e32 v9, v205
	v_mov_b32_e32 v10, v206
	v_mov_b32_e32 v11, v207
	v_mov_b32_e32 v4, v208
	v_mov_b32_e32 v5, v209
	v_mov_b32_e32 v6, v210
	v_mov_b32_e32 v7, v211
	v_mov_b32_e32 v12, v212
	v_mov_b32_e32 v13, v213
	v_mov_b32_e32 v14, v214
	v_mov_b32_e32 v15, v215
	v_mov_b32_e32 v44, v216
	v_mov_b32_e32 v45, v217
	v_mov_b32_e32 v46, v218
	v_mov_b32_e32 v47, v219
	v_mov_b32_e32 v40, v220
	v_mov_b32_e32 v41, v221
	v_mov_b32_e32 v42, v222
	v_mov_b32_e32 v43, v223
	v_mov_b32_e32 v36, v224
	v_mov_b32_e32 v37, v225
	v_mov_b32_e32 v38, v226
	v_mov_b32_e32 v39, v227
	v_mov_b32_e32 v32, v228
	v_mov_b32_e32 v33, v229
	v_mov_b32_e32 v34, v230
	v_mov_b32_e32 v35, v231
	v_mov_b32_e32 v28, v232
	v_mov_b32_e32 v29, v233
	v_mov_b32_e32 v30, v234
	v_mov_b32_e32 v31, v235
	v_mov_b32_e32 v24, v236
	v_mov_b32_e32 v25, v237
	v_mov_b32_e32 v26, v238
	v_mov_b32_e32 v27, v239
	v_mov_b32_e32 v20, v240
	v_mov_b32_e32 v21, v241
	v_mov_b32_e32 v22, v242
	v_mov_b32_e32 v23, v243
	v_mov_b32_e32 v16, v244
	v_mov_b32_e32 v17, v245
	v_mov_b32_e32 v18, v246
	v_mov_b32_e32 v19, v247
	v_cndmask_b32_e64 v49, 0, 1, s[52:53]
	v_mov_b32_e32 v48, 0
	v_cmp_ne_u32_e64 s[26:27], 1, v49
	v_mov_b32_e32 v54, 0
	v_mov_b32_e32 v55, 0
	v_mov_b32_e32 v56, 0
	v_mov_b32_e32 v57, 0
	s_and_saveexec_b64 s[38:39], s[6:7]
	s_cbranch_execz .LBB0_764
	ds_read_b64 v[50:51], v64
	s_waitcnt vmcnt(0)
	v_lshlrev_b32_e32 v49, 16, v44
	v_and_b32_e32 v52, 0xffff0000, v44
	v_lshlrev_b32_e32 v44, 16, v45
	v_and_b32_e32 v45, 0xffff0000, v45
	v_lshlrev_b32_e32 v54, 16, v46
	v_and_b32_e32 v55, 0xffff0000, v46
	v_lshlrev_b32_e32 v56, 16, v47
	v_and_b32_e32 v57, 0xffff0000, v47
	s_waitcnt lgkmcnt(0)
	v_sub_f32_e32 v45, v45, v50
	v_sub_f32_e32 v44, v44, v50
	v_sub_f32_e32 v47, v52, v50
	v_sub_f32_e32 v46, v49, v50
	v_pk_mul_f32 v[52:53], v[50:51], v[46:47] op_sel:[1,0]
	v_pk_mul_f32 v[44:45], v[50:51], v[44:45] op_sel:[1,0]
	v_sub_f32_e32 v55, v55, v50
	v_pk_fma_f32 v[46:47], v[10:11], v[44:45], v[14:15]
	v_pk_fma_f32 v[44:45], v[8:9], v[52:53], v[12:13]
	v_sub_f32_e32 v53, v57, v50
	v_sub_f32_e32 v52, v56, v50
	v_sub_f32_e32 v54, v54, v50
	v_pk_mul_f32 v[54:55], v[50:51], v[54:55] op_sel:[1,0]
	v_pk_mul_f32 v[50:51], v[50:51], v[52:53] op_sel:[1,0]
	s_and_b64 vcc, exec, s[26:27]
	v_pk_fma_f32 v[52:53], v[2:3], v[50:51], v[6:7]
	v_pk_fma_f32 v[50:51], v[0:1], v[54:55], v[4:5]
	s_cbranch_vccnz .LBB0_763
	s_load_dwordx2 s[60:61], s[0:1], 0xd0
	s_waitcnt lgkmcnt(0)
	v_lshl_add_u64 v[54:55], s[60:61], 0, v[72:73]
	v_lshl_add_u64 v[54:55], v[54:55], 0, s[36:37]
	v_add_co_u32_e32 v54, vcc, 0x19320000, v54
	s_nop 1
	v_addc_co_u32_e32 v55, vcc, 0, v55, vcc
	global_store_dwordx4 v[54:55], v[44:47], off
	global_store_dwordx4 v[54:55], v[50:53], off offset:16

.LBB0_792:
	s_or_b64 exec, exec, s[38:39]
	v_lshl_add_u64 v[110:111], s[42:43], 0, v[70:71]
	v_add_co_u32_e32 v0, vcc, 0x3600000, v110
	ds_write_b128 v130, v[24:27] offset:60928
	s_nop 0
	v_addc_co_u32_e32 v1, vcc, 0, v111, vcc
	v_add_co_u32_e32 v4, vcc, 0x3601000, v110
	s_waitcnt lgkmcnt(0)
	s_nop 0
	v_addc_co_u32_e32 v5, vcc, 0, v111, vcc
	s_barrier
	s_add_u32 s100, s36, 0x400
	s_addc_u32 s101, s37, 0
	s_cmp_eq_u32 s100, s99
	s_cbranch_scc1 .Lgpf_skip_b
	v_lshl_add_u64 v[248:249], v[68:69], 0, s[100:101]
	v_lshl_add_u64 v[250:251], v[88:89], 0, s[100:101]
	global_load_dwordx4 v[200:203], v[248:249], off
	global_load_dwordx4 v[204:207], v[248:249], off offset:-16
	global_load_dwordx4 v[208:211], v[250:251], off
	global_load_dwordx4 v[212:215], v[250:251], off offset:-16
	v_mov_b32_e32 v216, 0
	v_mov_b32_e32 v217, 0
	v_mov_b32_e32 v218, 0
	v_mov_b32_e32 v219, 0
	s_and_saveexec_b64 s[100:101], s[6:7]
	v_lshl_add_u64 v[252:253], s[42:43], 0, v[106:107]
	global_load_dwordx4 v[216:219], v[252:253], off offset:512
	s_or_b64 exec, exec, s[100:101]
	v_mov_b32_e32 v220, 0
	v_mov_b32_e32 v221, 0
	v_mov_b32_e32 v222, 0
	v_mov_b32_e32 v223, 0
	s_and_saveexec_b64 s[100:101], s[8:9]
	v_lshl_add_u64 v[252:253], s[42:43], 0, v[104:105]
	global_load_dwordx4 v[220:223], v[252:253], off offset:512
	s_or_b64 exec, exec, s[100:101]
	v_mov_b32_e32 v224, 0
	v_mov_b32_e32 v225, 0
	v_mov_b32_e32 v226, 0
	v_mov_b32_e32 v227, 0
	s_and_saveexec_b64 s[100:101], s[10:11]
	v_lshl_add_u64 v[252:253], s[42:43], 0, v[102:103]
	global_load_dwordx4 v[224:227], v[252:253], off offset:512
	s_or_b64 exec, exec, s[100:101]
	v_mov_b32_e32 v228, 0
	v_mov_b32_e32 v229, 0
	v_mov_b32_e32 v230, 0
	v_mov_b32_e32 v231, 0
	s_and_saveexec_b64 s[100:101], s[12:13]
	v_lshl_add_u64 v[252:253], s[42:43], 0, v[100:101]
	global_load_dwordx4 v[228:231], v[252:253], off offset:512
	s_or_b64 exec, exec, s[100:101]
	v_mov_b32_e32 v232, 0
	v_mov_b32_e32 v233, 0
	v_mov_b32_e32 v234, 0
	v_mov_b32_e32 v235, 0
	s_and_saveexec_b64 s[100:101], s[14:15]
	v_lshl_add_u64 v[252:253], s[42:43], 0, v[98:99]
	global_load_dwordx4 v[232:235], v[252:253], off offset:512
	s_or_b64 exec, exec, s[100:101]
	v_mov_b32_e32 v236, 0
	v_mov_b32_e32 v237, 0
	v_mov_b32_e32 v238, 0
	v_mov_b32_e32 v239, 0
	s_and_saveexec_b64 s[100:101], s[16:17]
	v_lshl_add_u64 v[252:253], s[42:43], 0, v[96:97]
	global_load_dwordx4 v[236:239], v[252:253], off offset:512
	s_or_b64 exec, exec, s[100:101]
	v_mov_b32_e32 v240, 0
	v_mov_b32_e32 v241, 0
	v_mov_b32_e32 v242, 0
	v_mov_b32_e32 v243, 0
	s_and_saveexec_b64 s[100:101], s[18:19]
	v_lshl_add_u64 v[252:253], s[42:43], 0, v[92:93]
	global_load_dwordx4 v[240:243], v[252:253], off offset:512
	s_or_b64 exec, exec, s[100:101]
	v_mov_b32_e32 v244, 0
	v_mov_b32_e32 v245, 0
	v_mov_b32_e32 v246, 0
	v_mov_b32_e32 v247, 0
	s_and_saveexec_b64 s[100:101], s[20:21]
	v_lshl_add_u64 v[252:253], s[42:43], 0, v[90:91]
	global_load_dwordx4 v[244:247], v[252:253], off offset:512
	s_or_b64 exec, exec, s[100:101]
.Lgpf_skip_b:
	global_load_dwordx4 v[0:3], v[0:1], off
	s_andn2_b64 vcc, exec, s[54:55]
	global_load_dwordx4 v[132:135], v[4:5], off
	ds_read_b64_tr_b16 v[4:5], v122
	ds_read_b64_tr_b16 v[6:7], v122 offset:2176
	ds_read_b64_tr_b16 v[10:11], v122 offset:2208
	ds_read_b64_tr_b16 v[8:9], v122 offset:32
	ds_read_b64_tr_b16 v[12:13], v122 offset:64
	ds_read_b64_tr_b16 v[16:17], v122 offset:96
	ds_read_b64_tr_b16 v[14:15], v122 offset:2240
	ds_read_b64_tr_b16 v[18:19], v122 offset:2272
	ds_read_b64_tr_b16 v[136:137], v122 offset:128
	ds_read_b64_tr_b16 v[138:139], v122 offset:2304
	ds_read_b64_tr_b16 v[142:143], v122 offset:2336
	ds_read_b64_tr_b16 v[140:141], v122 offset:160
	ds_read_b64_tr_b16 v[144:145], v122 offset:192
	ds_read_b64_tr_b16 v[148:149], v122 offset:224
	ds_read_b64_tr_b16 v[146:147], v122 offset:2368
	ds_read_b64_tr_b16 v[150:151], v122 offset:2400
	s_waitcnt vmcnt(1) lgkmcnt(14)
	v_mfma_f32_16x16x32_bf16 v[40:43], v[4:7], v[0:3], 0
	s_waitcnt lgkmcnt(12)
	v_mfma_f32_16x16x32_bf16 v[36:39], v[8:11], v[0:3], 0
	s_waitcnt lgkmcnt(9)
	v_mfma_f32_16x16x32_bf16 v[44:47], v[12:15], v[0:3], 0
	s_waitcnt lgkmcnt(8)
	v_mfma_f32_16x16x32_bf16 v[48:51], v[16:19], v[0:3], 0
	s_waitcnt lgkmcnt(6)
	v_mfma_f32_16x16x32_bf16 v[60:63], v[136:139], v[0:3], 0
	s_waitcnt lgkmcnt(4)
	v_mfma_f32_16x16x32_bf16 v[56:59], v[140:143], v[0:3], 0
	s_waitcnt lgkmcnt(1)
	v_mfma_f32_16x16x32_bf16 v[52:55], v[144:147], v[0:3], 0
	s_waitcnt lgkmcnt(0)
	v_mfma_f32_16x16x32_bf16 v[32:35], v[148:151], v[0:3], 0
	s_waitcnt vmcnt(0)
	v_mfma_f32_16x16x32_bf16 v[28:31], v[4:7], v[132:135], 0
	v_mfma_f32_16x16x32_bf16 v[24:27], v[8:11], v[132:135], 0
	v_mfma_f32_16x16x32_bf16 v[20:23], v[12:15], v[132:135], 0
	v_mfma_f32_16x16x32_bf16 v[16:19], v[16:19], v[132:135], 0
	v_mfma_f32_16x16x32_bf16 v[12:15], v[136:139], v[132:135], 0
	v_mfma_f32_16x16x32_bf16 v[8:11], v[140:143], v[132:135], 0
	v_mfma_f32_16x16x32_bf16 v[4:7], v[144:147], v[132:135], 0
	v_mfma_f32_16x16x32_bf16 v[0:3], v[148:151], v[132:135], 0
	s_cbranch_vccnz .LBB0_794
	v_add_co_u32_e32 v132, vcc, 0x3600000, v110
	s_nop 1
	v_addc_co_u32_e32 v133, vcc, 0, v111, vcc
	v_add_co_u32_e32 v136, vcc, 0x3601000, v110
	global_load_dwordx4 v[132:135], v[132:133], off offset:64
	s_nop 0
	v_addc_co_u32_e32 v137, vcc, 0, v111, vcc
	global_load_dwordx4 v[136:139], v[136:137], off offset:64
	ds_read_b64_tr_b16 v[140:141], v122 offset:17408
	ds_read_b64_tr_b16 v[142:143], v122 offset:19584
	ds_read_b64_tr_b16 v[146:147], v122 offset:19616
	ds_read_b64_tr_b16 v[144:145], v122 offset:17440
	ds_read_b64_tr_b16 v[148:149], v122 offset:17472
	ds_read_b64_tr_b16 v[152:153], v122 offset:17504
	ds_read_b64_tr_b16 v[150:151], v122 offset:19648
	ds_read_b64_tr_b16 v[154:155], v122 offset:19680
	ds_read_b64_tr_b16 v[156:157], v122 offset:17536
	ds_read_b64_tr_b16 v[158:159], v122 offset:19712
	ds_read_b64_tr_b16 v[162:163], v122 offset:19744
	ds_read_b64_tr_b16 v[160:161], v122 offset:17568
	ds_read_b64_tr_b16 v[164:165], v122 offset:17600
	ds_read_b64_tr_b16 v[168:169], v122 offset:17632
	ds_read_b64_tr_b16 v[166:167], v122 offset:19776
	ds_read_b64_tr_b16 v[170:171], v122 offset:19808
	s_waitcnt vmcnt(1) lgkmcnt(14)
	v_mfma_f32_16x16x32_bf16 v[40:43], v[140:143], v[132:135], v[40:43]
	s_waitcnt lgkmcnt(12)
	v_mfma_f32_16x16x32_bf16 v[36:39], v[144:147], v[132:135], v[36:39]
	s_waitcnt lgkmcnt(9)
	v_mfma_f32_16x16x32_bf16 v[44:47], v[148:151], v[132:135], v[44:47]
	s_waitcnt lgkmcnt(8)
	v_mfma_f32_16x16x32_bf16 v[48:51], v[152:155], v[132:135], v[48:51]
	s_waitcnt lgkmcnt(6)
	v_mfma_f32_16x16x32_bf16 v[60:63], v[156:159], v[132:135], v[60:63]
	s_waitcnt lgkmcnt(4)
	v_mfma_f32_16x16x32_bf16 v[56:59], v[160:163], v[132:135], v[56:59]
	s_waitcnt lgkmcnt(1)
	v_mfma_f32_16x16x32_bf16 v[52:55], v[164:167], v[132:135], v[52:55]
	s_waitcnt lgkmcnt(0)
	v_mfma_f32_16x16x32_bf16 v[32:35], v[168:171], v[132:135], v[32:35]
	s_waitcnt vmcnt(0)
	v_mfma_f32_16x16x32_bf16 v[28:31], v[140:143], v[136:139], v[28:31]
	v_mfma_f32_16x16x32_bf16 v[24:27], v[144:147], v[136:139], v[24:27]
	v_mfma_f32_16x16x32_bf16 v[20:23], v[148:151], v[136:139], v[20:23]
	v_mfma_f32_16x16x32_bf16 v[16:19], v[152:155], v[136:139], v[16:19]
	v_mfma_f32_16x16x32_bf16 v[12:15], v[156:159], v[136:139], v[12:15]
	v_mfma_f32_16x16x32_bf16 v[8:11], v[160:163], v[136:139], v[8:11]
	v_mfma_f32_16x16x32_bf16 v[4:7], v[164:167], v[136:139], v[4:7]
	v_mfma_f32_16x16x32_bf16 v[0:3], v[168:171], v[136:139], v[0:3]
